# pro1: stack4 + 8-phase GEMM prologues (P1 first unit, pw, P4, P5 sample): second DMA batch issued before the wait on the first (vmcnt(2)+barrier -> vmcnt(8)+barrier after the 6 loads)
# baseline (speedup 1.0000x reference)
.LBB0_92:
	s_add_u32 s0, s92, 0x3400000
	v_writelane_b32 v247, s0, 24
	s_addc_u32 s0, s93, 0
	s_add_u32 s82, s92, 0x4600000
	s_addc_u32 s83, s93, 0
	v_writelane_b32 v247, s0, 26
	s_add_u32 s0, s92, 0x5800000
	v_writelane_b32 v247, s0, 27
	s_addc_u32 s0, s93, 0
	s_add_u32 s48, s92, 0x6a00000
	s_addc_u32 s49, s93, 0
	v_writelane_b32 v247, s0, 29
	s_add_u32 s0, s92, 0x7c00000
	s_addc_u32 s1, s93, 0
	v_writelane_b32 v247, s0, 31
	s_andn2_b64 vcc, exec, s[4:5]
	s_nop 0
	v_writelane_b32 v247, s1, 32
	v_writelane_b32 v247, s91, 33
	v_writelane_b32 v247, s94, 34
	v_writelane_b32 v247, s92, 35
	s_nop 1
	v_writelane_b32 v247, s93, 36
	s_cbranch_vccnz .LBB0_272
	v_ashrrev_i32_e32 v1, 31, v8
	v_lshrrev_b32_e32 v1, 26, v1
	v_add_u32_e32 v1, v8, v1
	v_ashrrev_i32_e32 v9, 6, v1
	v_bfe_i32 v1, v8, 27, 1
	v_lshlrev_b32_e32 v0, 4, v8
	v_lshrrev_b32_e32 v1, 22, v1
	v_add_u32_e32 v1, v0, v1
	v_and_b32_e32 v1, 0xfffffc00, v1
	v_sub_u32_e32 v1, v0, v1
	v_lshrrev_b32_e32 v2, 4, v1
	v_bitop3_b32 v1, v2, v1, 32 bitop3:0x6c
	v_ashrrev_i32_e32 v3, 31, v1
	v_lshrrev_b32_e32 v3, 26, v3
	v_add_u32_e32 v3, v1, v3
	v_lshlrev_b32_e32 v2, 3, v9
	v_ashrrev_i32_e32 v10, 6, v3
	v_and_b32_e32 v3, 0xc0, v3
	v_and_b32_e32 v2, -16, v2
	v_sub_u32_e32 v1, v1, v3
	v_mov_b32_e32 v3, 1
	v_add_u32_e32 v2, v10, v2
	v_ashrrev_i16_sdwa v1, v3, sext(v1) dst_sel:DWORD dst_unused:UNUSED_PAD src0_sel:DWORD src1_sel:BYTE_0
	v_lshlrev_b32_e32 v4, 5, v9
	v_bfe_i32 v11, v1, 0, 16
	v_lshlrev_b32_e32 v1, 1, v2
	v_lshrrev_b32_e32 v5, 2, v2
	v_and_b32_e32 v6, 3, v10
	s_mov_b32 s1, 0x1fffe0
	v_and_b32_e32 v4, 32, v4
	v_and_b32_e32 v1, 24, v1
	v_and_b32_e32 v5, 4, v5
	v_and_or_b32 v6, v2, s1, v6
	v_or3_b32 v1, v6, v5, v1
	v_add_lshl_u32 v4, v4, v11, 1
	v_add_u32_e32 v0, 0x2000, v0
	v_lshl_add_u32 v138, v1, 11, v4
	v_ashrrev_i32_e32 v1, 31, v0
	v_lshrrev_b32_e32 v1, 22, v1
	v_add_u32_e32 v1, v0, v1
	s_waitcnt vmcnt(0)
	v_ashrrev_i32_e32 v12, 10, v1
	v_mul_i32_i24_e32 v1, 0x400, v12
	v_sub_u32_e32 v0, v0, v1
	v_lshrrev_b32_e32 v1, 4, v0
	v_bitop3_b32 v0, v1, v0, 32 bitop3:0x6c
	v_lshl_add_u32 v136, v2, 11, v4
	v_ashrrev_i32_e32 v2, 31, v0
	v_lshrrev_b32_e32 v2, 26, v2
	v_add_u32_e32 v2, v0, v2
	v_lshlrev_b32_e32 v1, 3, v12
	v_ashrrev_i32_e32 v13, 6, v2
	v_and_b32_e32 v2, 0xc0, v2
	v_and_b32_e32 v1, -16, v1
	v_sub_u32_e32 v0, v0, v2
	v_add_u32_e32 v1, v13, v1
	v_ashrrev_i16_sdwa v0, v3, sext(v0) dst_sel:DWORD dst_unused:UNUSED_PAD src0_sel:DWORD src1_sel:BYTE_0
	v_and_b32_e32 v3, 3, v13
	v_and_or_b32 v3, v1, s1, v3
	s_ashr_i32 s1, s22, 6
	s_ashr_i32 s17, s16, 31
	s_ashr_i32 s3, s2, 31
	s_ashr_i32 s0, s22, 8
	s_lshl_b32 s23, s1, 10
	s_lshl_b64 s[4:5], s[16:17], 19
	s_lshl_b64 s[6:7], s[2:3], 19
	s_add_u32 s6, s89, s6
	v_lshlrev_b32_e32 v4, 5, v12
	v_bfe_i32 v14, v0, 0, 16
	v_lshlrev_b32_e32 v0, 1, v1
	v_lshrrev_b32_e32 v2, 2, v1
	s_addc_u32 s7, s90, s7
	s_add_i32 s50, s23, 0
	v_and_b32_e32 v4, 32, v4
	v_and_b32_e32 v0, 24, v0
	v_and_b32_e32 v2, 4, v2
	s_add_i32 m0, s50, 0x10000
	v_or3_b32 v0, v3, v2, v0
	v_add_lshl_u32 v2, v4, v14, 1
	global_load_lds_dwordx4 v138, s[6:7]
	s_add_i32 m0, s50, 0x12000
	v_lshl_add_u32 v142, v0, 11, v2
	s_add_u32 s8, s6, 0x40000
	global_load_lds_dwordx4 v142, s[6:7]
	s_addc_u32 s9, s7, 0
	s_add_i32 m0, s50, 0x14000
	v_lshl_add_u32 v140, v1, 11, v2
	global_load_lds_dwordx4 v138, s[8:9]
	s_add_i32 m0, s50, 0x16000
	s_add_u32 s4, s12, s4
	s_addc_u32 s5, s13, s5
	s_add_i32 s51, s50, 0x2000
	global_load_lds_dwordx4 v142, s[8:9]
	s_mov_b32 m0, s50
	s_add_u32 s8, s4, 0x40000
	global_load_lds_dwordx4 v136, s[4:5]
	s_mov_b32 m0, s51
	s_addc_u32 s9, s5, 0
	s_add_i32 s71, s50, 0x4000
	global_load_lds_dwordx4 v140, s[4:5]
	s_mov_b32 m0, s71
	s_add_i32 s80, s50, 0x6000
	global_load_lds_dwordx4 v136, s[8:9]
	s_mov_b32 m0, s80
	v_mov_b32_e32 v145, 0
	global_load_lds_dwordx4 v140, s[8:9]
	v_mov_b32_e32 v139, v145
	v_mov_b32_e32 v143, v145
	v_mov_b32_e32 v137, v145
	v_mov_b32_e32 v141, v145
	s_mov_b32 s15, 0
	v_lshl_add_u64 v[6:7], s[6:7], 0, v[138:139]
	v_lshl_add_u64 v[4:5], s[6:7], 0, v[142:143]
	v_lshl_add_u64 v[2:3], s[4:5], 0, v[136:137]
	s_cmp_lg_u32 s0, 1
	s_cselect_b64 vcc, -1, 0
	v_lshl_add_u64 v[0:1], s[4:5], 0, v[140:141]
	v_writelane_b32 v247, s95, 37
.LBB0_95:
	s_lshl_b32 s81, s0, 6
	s_lshl_b32 s3, s0, 13
	s_lshl_b32 s0, s1, 5
	s_mov_b64 s[30:31], 0x80
	s_and_b32 s8, s0, 0x60
	s_add_i32 m0, s50, 0x18000
	v_lshl_add_u64 v[6:7], v[6:7], 0, s[30:31]
	s_lshl_b32 s9, s8, 7
	global_load_lds_dwordx4 v[6:7], off
	v_lshl_add_u64 v[4:5], v[4:5], 0, s[30:31]
	s_add_i32 m0, s50, 0x1a000
	s_add_i32 s91, s50, 0x8000
	s_add_i32 s92, s50, 0xa000
	global_load_lds_dwordx4 v[4:5], off
	v_lshl_add_u64 v[2:3], v[2:3], 0, s[30:31]
	s_mov_b32 m0, s91
	s_add_u32 s0, s6, 0x40080
	global_load_lds_dwordx4 v[2:3], off
	v_lshl_add_u64 v[0:1], v[0:1], 0, s[30:31]
	s_mov_b32 m0, s92
	s_addc_u32 s1, s7, 0
	global_load_lds_dwordx4 v[0:1], off
	s_add_i32 m0, s50, 0x1c000
	v_lshl_add_u64 v[0:1], s[0:1], 0, v[138:139]
	global_load_lds_dwordx4 v[0:1], off
	v_lshl_add_u64 v[0:1], s[0:1], 0, v[142:143]
	s_add_i32 m0, s50, 0x1e000
	v_and_b32_e32 v147, 15, v8
	global_load_lds_dwordx4 v[0:1], off
	s_cbranch_vccnz .Lpro_skip0
	s_barrier
.Lpro_skip0:
	s_waitcnt vmcnt(8)
	s_barrier
	v_lshrrev_b32_e32 v0, 1, v8
	v_and_b32_e32 v0, 24, v0
	v_lshlrev_b32_e32 v1, 1, v0
	v_or_b32_e32 v146, s8, v0
	v_and_b32_e32 v0, 7, v8
	v_lshlrev_b32_e32 v2, 2, v8
	v_add_u32_e32 v148, 0x405a, v0
	v_add_u32_e32 v150, 22, v0
	v_lshlrev_b32_e32 v0, 14, v9
	v_lshl_or_b32 v1, v147, 6, v1
	v_and_b32_e32 v2, 32, v2
	v_and_b32_e32 v0, 0xffff8000, v0
	v_bitop3_b32 v3, v1, s3, v2 bitop3:0xde
	v_bitop3_b32 v149, v1, s9, v2 bitop3:0xde
	v_lshl_add_u32 v0, v10, 11, v0
	v_and_b32_e32 v1, 1, v9
	v_lshl_or_b32 v0, v1, 6, v0
	v_lshl_add_u32 v154, v11, 1, v0
	v_lshlrev_b32_e32 v0, 14, v12
	v_and_b32_e32 v0, 0xffff8000, v0
	s_waitcnt vmcnt(6)
	v_readlane_b32 s0, v247, 10
	v_lshl_add_u32 v0, v13, 11, v0
	v_and_b32_e32 v1, 1, v12
	s_ashr_i32 s93, s0, 31
	v_readlane_b32 s0, v247, 11
	v_lshlrev_b32_e32 v144, 1, v146
	v_lshl_or_b32 v0, v1, 6, v0
	s_add_i32 s95, 0, 0x10000
	s_add_i32 s96, 0, 0x14000
	v_mov_b32_e32 v151, v145
	s_ashr_i32 s94, s0, 31
	v_lshl_add_u64 v[152:153], s[10:11], 0, v[144:145]
	v_mov_b32_e32 v155, v145
	v_lshl_add_u32 v156, v14, 1, v0
	v_mov_b32_e32 v157, v145
	v_mov_b64_e32 v[158:159], 0x3b8
	v_mov_b64_e32 v[160:161], 0x3b7
	v_add_u32_e32 v170, s95, v149
	v_add_u32_e32 v171, s96, v149
	v_add_u32_e32 v172, 0, v3
	s_movk_i32 s97, 0x3fff
	s_mov_b64 s[34:35], 0x2207800
	s_mov_b64 s[68:69], 0x2100000
	s_mov_b32 s70, 0x3e38aa3b
	s_mov_b32 s25, 0
	s_barrier
	s_branch .LBB0_98

.LBB0_570:
	s_add_i32 s0, 0, 0x20170
	v_mov_b32_e32 v0, s0
	s_waitcnt lgkmcnt(0)
	s_barrier
	ds_read_b32 v0, v0
	s_add_u32 s30, s66, 0xec00000
	s_addc_u32 s31, s67, 0
	s_waitcnt lgkmcnt(0)
	v_readfirstlane_b32 s2, v0
	v_mbcnt_lo_u32_b32 v0, -1, 0
	v_mbcnt_hi_u32_b32 v0, -1, v0
	s_cmpk_gt_i32 s2, 0x87
	v_add_u32_e32 v11, s94, v0
	s_nop 0
	v_readfirstlane_b32 s18, v11
	s_cbranch_scc1 .LBB0_578
	v_lshlrev_b32_e32 v0, 4, v11
	v_add_u32_e32 v1, 0x2000, v0
	v_ashrrev_i32_e32 v2, 31, v1
	v_lshrrev_b32_e32 v2, 22, v2
	v_add_u32_e32 v2, v1, v2
	v_ashrrev_i32_e32 v8, 10, v2
	v_mul_i32_i24_e32 v2, 0x400, v8
	v_sub_u32_e32 v1, v1, v2
	v_lshrrev_b32_e32 v2, 4, v1
	v_bitop3_b32 v1, v2, v1, 32 bitop3:0x6c
	v_ashrrev_i32_e32 v2, 31, v1
	v_lshrrev_b32_e32 v2, 26, v2
	v_add_u32_e32 v2, v1, v2
	v_lshlrev_b32_e32 v3, 3, v8
	v_ashrrev_i32_e32 v9, 6, v2
	v_and_b32_e32 v3, -16, v3
	v_add_u32_e32 v3, v9, v3
	v_and_b32_e32 v4, 3, v9
	s_mov_b32 s3, 0x3fffe0
	v_lshrrev_b32_e32 v5, 2, v3
	v_lshlrev_b32_e32 v6, 1, v3
	v_and_b32_e32 v2, 0xc0, v2
	v_and_or_b32 v4, v3, s3, v4
	v_and_b32_e32 v5, 4, v5
	v_and_b32_e32 v6, 24, v6
	v_sub_u32_e32 v1, v1, v2
	v_mov_b32_e32 v2, 1
	v_or3_b32 v4, v4, v5, v6
	v_lshlrev_b32_e32 v5, 5, v8
	v_ashrrev_i16_sdwa v1, v2, sext(v1) dst_sel:DWORD dst_unused:UNUSED_PAD src0_sel:DWORD src1_sel:BYTE_0
	v_and_b32_e32 v5, 32, v5
	v_bfe_i32 v10, v1, 0, 16
	v_add_lshl_u32 v1, v5, v10, 1
	v_lshl_add_u32 v88, v4, 10, v1
	v_lshl_add_u32 v90, v3, 10, v1
	v_bfe_i32 v1, v11, 27, 1
	v_lshrrev_b32_e32 v1, 22, v1
	v_add_u32_e32 v1, v0, v1
	v_and_b32_e32 v1, 0xfffffc00, v1
	v_sub_u32_e32 v0, v0, v1
	v_lshrrev_b32_e32 v1, 4, v0
	v_ashrrev_i32_e32 v3, 31, v11
	v_bitop3_b32 v0, v1, v0, 32 bitop3:0x6c
	v_lshrrev_b32_e32 v3, 26, v3
	v_ashrrev_i32_e32 v1, 31, v0
	v_add_u32_e32 v3, v11, v3
	v_lshrrev_b32_e32 v1, 26, v1
	v_ashrrev_i32_e32 v13, 6, v3
	v_add_u32_e32 v1, v0, v1
	v_lshlrev_b32_e32 v3, 3, v13
	v_ashrrev_i32_e32 v12, 6, v1
	v_and_b32_e32 v3, -16, v3
	s_and_b32 s1, s2, 1
	s_ashr_i32 s2, s2, 1
	v_add_u32_e32 v3, v12, v3
	v_and_b32_e32 v4, 3, v12
	s_ashr_i32 s8, s18, 6
	v_and_or_b32 v4, v3, s3, v4
	s_ashr_i32 s3, s2, 31
	s_ashr_i32 s9, s18, 8
	s_lshl_b32 s14, s8, 10
	v_lshrrev_b32_e32 v5, 2, v3
	v_lshlrev_b32_e32 v6, 1, v3
	v_and_b32_e32 v1, 0xc0, v1
	s_lshl_b64 s[10:11], s[2:3], 18
	s_lshl_b32 s12, s1, 18
	v_and_b32_e32 v5, 4, v5
	v_and_b32_e32 v6, 24, v6
	v_sub_u32_e32 v0, v0, v1
	s_add_u32 s6, s66, s12
	v_or3_b32 v4, v4, v5, v6
	v_lshlrev_b32_e32 v5, 5, v13
	v_ashrrev_i16_sdwa v0, v2, sext(v0) dst_sel:DWORD dst_unused:UNUSED_PAD src0_sel:DWORD src1_sel:BYTE_0
	s_addc_u32 s7, s67, 0
	v_and_b32_e32 v5, 32, v5
	v_bfe_i32 v14, v0, 0, 16
	s_add_u32 s4, s6, 0xa00000
	v_add_lshl_u32 v0, v5, v14, 1
	s_addc_u32 s5, s7, 0
	s_add_i32 s3, s14, 0
	v_lshl_add_u32 v92, v4, 10, v0
	s_add_i32 m0, s3, 0x10000
	v_lshl_add_u32 v94, v3, 10, v0
	global_load_lds_dwordx4 v92, s[4:5]
	s_add_i32 m0, s3, 0x12000
	s_add_u32 s6, s6, 0xa20000
	global_load_lds_dwordx4 v88, s[4:5]
	s_addc_u32 s7, s7, 0
	s_add_i32 m0, s3, 0x14000
	v_mov_b32_e32 v93, 0
	global_load_lds_dwordx4 v92, s[6:7]
	s_add_i32 m0, s3, 0x16000
	v_mov_b32_e32 v89, v93
	global_load_lds_dwordx4 v88, s[6:7]
	v_readlane_b32 s6, v247, 38
	v_readlane_b32 s7, v247, 39
	s_add_u32 s6, s6, s10
	s_addc_u32 s7, s7, s11
	s_add_i32 s19, s3, 0x2000
	s_mov_b32 m0, s3
	s_add_u32 s16, s6, 0x20000
	global_load_lds_dwordx4 v94, s[6:7]
	s_mov_b32 m0, s19
	s_addc_u32 s17, s7, 0
	s_add_i32 s20, s3, 0x4000
	global_load_lds_dwordx4 v90, s[6:7]
	s_mov_b32 m0, s20
	s_add_i32 s21, s3, 0x6000
	global_load_lds_dwordx4 v94, s[16:17]
	s_mov_b32 m0, s21
	v_mov_b32_e32 v95, v93
	global_load_lds_dwordx4 v90, s[16:17]
	v_mov_b32_e32 v91, v93
	v_lshl_add_u64 v[6:7], s[4:5], 0, v[92:93]
	v_lshl_add_u64 v[4:5], s[4:5], 0, v[88:89]
	v_lshl_add_u64 v[2:3], s[6:7], 0, v[94:95]
	s_cmp_lg_u32 s9, 1
	s_cselect_b64 vcc, -1, 0
	v_lshl_add_u64 v[0:1], s[6:7], 0, v[90:91]
.LBB0_573:
	v_lshrrev_b32_e32 v16, 1, v11
	v_and_b32_e32 v109, 24, v16
	s_lshl_b32 s8, s8, 5
	v_and_b32_e32 v15, 15, v11
	v_lshlrev_b32_e32 v16, 1, v109
	v_lshlrev_b32_e32 v11, 2, v11
	s_and_b32 s22, s8, 0x60
	v_lshl_or_b32 v108, s9, 6, v15
	v_lshl_or_b32 v15, v15, 6, v16
	s_lshl_b32 s9, s9, 13
	v_and_b32_e32 v11, 32, v11
	s_lshl_b32 s8, s22, 7
	v_bitop3_b32 v16, v15, s9, v11 bitop3:0xde
	v_bitop3_b32 v11, v15, s8, v11 bitop3:0xde
	s_mov_b64 s[8:9], 0x80
	s_add_i32 m0, s3, 0x18000
	v_lshl_add_u64 v[6:7], v[6:7], 0, s[8:9]
	global_load_lds_dwordx4 v[6:7], off
	v_lshl_add_u64 v[4:5], v[4:5], 0, s[8:9]
	s_add_i32 m0, s3, 0x1a000
	s_add_i32 s23, s3, 0x8000
	s_add_i32 s24, s3, 0xa000
	global_load_lds_dwordx4 v[4:5], off
	v_lshl_add_u64 v[2:3], v[2:3], 0, s[8:9]
	s_mov_b32 m0, s23
	s_add_u32 s16, s4, 0x20080
	global_load_lds_dwordx4 v[2:3], off
	v_lshl_add_u64 v[0:1], v[0:1], 0, s[8:9]
	s_mov_b32 m0, s24
	s_addc_u32 s17, s5, 0
	global_load_lds_dwordx4 v[0:1], off
	s_add_i32 m0, s3, 0x1c000
	v_lshl_add_u64 v[0:1], s[16:17], 0, v[92:93]
	global_load_lds_dwordx4 v[0:1], off
	v_lshl_add_u64 v[0:1], s[16:17], 0, v[88:89]
	s_add_i32 m0, s3, 0x1e000
	s_add_u32 s10, s66, s10
	global_load_lds_dwordx4 v[0:1], off
	s_cbranch_vccnz .Lpro_skip1
	s_barrier
.Lpro_skip1:
	s_waitcnt vmcnt(8)
	s_barrier
	v_lshlrev_b32_e32 v0, 13, v13
	v_and_b32_e32 v0, 0xffffc000, v0
	v_lshl_add_u32 v0, v12, 10, v0
	v_and_b32_e32 v1, 1, v13
	v_lshl_or_b32 v0, v1, 6, v0
	s_addc_u32 s11, s67, s11
	v_lshl_add_u32 v0, v14, 1, v0
	v_mov_b32_e32 v1, v93
	v_lshl_add_u64 v[0:1], s[10:11], 0, v[0:1]
	s_mov_b64 s[16:17], 0xba20080
	v_lshl_add_u64 v[104:105], v[0:1], 0, s[16:17]
	v_lshlrev_b32_e32 v0, 13, v8
	v_and_b32_e32 v0, 0xffffc000, v0
	s_add_u32 s12, s66, s12
	v_lshl_add_u32 v0, v9, 10, v0
	v_and_b32_e32 v1, 1, v8
	s_addc_u32 s13, s67, 0
	v_lshl_or_b32 v0, v1, 6, v0
	s_add_u32 s25, s12, 0xa00100
	s_waitcnt vmcnt(6)
	v_lshl_add_u32 v0, v10, 1, v0
	v_mov_b32_e32 v1, v93
	s_addc_u32 s26, s13, 0
	s_add_i32 s34, 0, 0x10000
	s_add_i32 s40, 0, 0x14000
	s_add_i32 s42, 0, 0x18000
	s_add_i32 s44, 0, 0x1c000
	v_lshl_add_u64 v[0:1], s[10:11], 0, v[0:1]
	v_add_u32_e32 v110, s34, v11
	v_add_u32_e32 v111, s40, v11
	s_add_i32 s34, s34, s14
	s_add_i32 s40, s40, s14
	v_add_u32_e32 v145, s42, v11
	v_add_u32_e32 v146, s44, v11
	s_add_i32 s42, s42, s14
	s_add_i32 s44, s44, s14
	v_lshl_add_u64 v[106:107], v[0:1], 0, s[16:17]
	s_mov_b32 s27, -2
	s_mov_b64 s[12:13], 0
	v_add_u32_e32 v144, 0, v16
	s_add_i32 s28, s3, 0xc000
	s_add_i32 s29, s3, 0xe000
	s_add_i32 s35, s34, 0x2000
	s_add_i32 s41, s40, 0x2000
	s_add_i32 s43, s42, 0x2000
	s_add_i32 s45, s44, 0x2000
	v_mov_b32_e32 v0, v93
	v_mov_b32_e32 v1, v93
	v_mov_b32_e32 v2, v93
	v_mov_b32_e32 v3, v93
	v_mov_b32_e32 v4, v93
	v_mov_b32_e32 v5, v93
	v_mov_b32_e32 v6, v93
	v_mov_b32_e32 v7, v93
	v_mov_b32_e32 v16, v93
	v_mov_b32_e32 v17, v93
	v_mov_b32_e32 v18, v93
	v_mov_b32_e32 v19, v93
	v_mov_b32_e32 v20, v93
	v_mov_b32_e32 v21, v93
	v_mov_b32_e32 v22, v93
	v_mov_b32_e32 v23, v93
	v_mov_b32_e32 v32, v93
	v_mov_b32_e32 v33, v93
	v_mov_b32_e32 v34, v93
	v_mov_b32_e32 v35, v93
	v_mov_b32_e32 v36, v93
	v_mov_b32_e32 v37, v93
	v_mov_b32_e32 v38, v93
	v_mov_b32_e32 v39, v93
	v_mov_b32_e32 v48, v93
	v_mov_b32_e32 v49, v93
	v_mov_b32_e32 v50, v93
	v_mov_b32_e32 v51, v93
	v_mov_b32_e32 v52, v93
	v_mov_b32_e32 v53, v93
	v_mov_b32_e32 v54, v93
	v_mov_b32_e32 v55, v93
	v_mov_b32_e32 v8, v93
	v_mov_b32_e32 v9, v93
	v_mov_b32_e32 v10, v93
	v_mov_b32_e32 v11, v93
	v_mov_b32_e32 v12, v93
	v_mov_b32_e32 v13, v93
	v_mov_b32_e32 v14, v93
	v_mov_b32_e32 v15, v93
	v_mov_b32_e32 v24, v93
	v_mov_b32_e32 v25, v93
	v_mov_b32_e32 v26, v93
	v_mov_b32_e32 v27, v93
	v_mov_b32_e32 v28, v93
	v_mov_b32_e32 v29, v93
	v_mov_b32_e32 v30, v93
	v_mov_b32_e32 v31, v93
	v_mov_b32_e32 v40, v93
	v_mov_b32_e32 v41, v93
	v_mov_b32_e32 v42, v93
	v_mov_b32_e32 v43, v93
	v_mov_b32_e32 v44, v93
	v_mov_b32_e32 v45, v93
	v_mov_b32_e32 v46, v93
	v_mov_b32_e32 v47, v93
	v_mov_b32_e32 v56, v93
	v_mov_b32_e32 v57, v93
	v_mov_b32_e32 v58, v93
	v_mov_b32_e32 v59, v93
	v_mov_b32_e32 v60, v93
	v_mov_b32_e32 v61, v93
	v_mov_b32_e32 v62, v93
	v_mov_b32_e32 v63, v93
	v_mov_b32_e32 v64, v93
	v_mov_b32_e32 v65, v93
	v_mov_b32_e32 v66, v93
	v_mov_b32_e32 v67, v93
	v_mov_b32_e32 v68, v93
	v_mov_b32_e32 v69, v93
	v_mov_b32_e32 v70, v93
	v_mov_b32_e32 v71, v93
	v_mov_b32_e32 v80, v93
	v_mov_b32_e32 v81, v93
	v_mov_b32_e32 v82, v93
	v_mov_b32_e32 v83, v93
	v_mov_b32_e32 v84, v93
	v_mov_b32_e32 v85, v93
	v_mov_b32_e32 v86, v93
	v_mov_b32_e32 v87, v93
	v_mov_b32_e32 v112, v93
	v_mov_b32_e32 v113, v93
	v_mov_b32_e32 v114, v93
	v_mov_b32_e32 v115, v93
	v_mov_b32_e32 v116, v93
	v_mov_b32_e32 v117, v93
	v_mov_b32_e32 v118, v93
	v_mov_b32_e32 v119, v93
	v_mov_b32_e32 v128, v93
	v_mov_b32_e32 v129, v93
	v_mov_b32_e32 v130, v93
	v_mov_b32_e32 v131, v93
	v_mov_b32_e32 v132, v93
	v_mov_b32_e32 v133, v93
	v_mov_b32_e32 v134, v93
	v_mov_b32_e32 v135, v93
	v_mov_b32_e32 v72, v93
	v_mov_b32_e32 v73, v93
	v_mov_b32_e32 v74, v93
	v_mov_b32_e32 v75, v93
	v_mov_b32_e32 v76, v93
	v_mov_b32_e32 v77, v93
	v_mov_b32_e32 v78, v93
	v_mov_b32_e32 v79, v93
	v_mov_b32_e32 v96, v93
	v_mov_b32_e32 v97, v93
	v_mov_b32_e32 v98, v93
	v_mov_b32_e32 v99, v93
	v_mov_b32_e32 v100, v93
	v_mov_b32_e32 v101, v93
	v_mov_b32_e32 v102, v93
	v_mov_b32_e32 v103, v93
	v_mov_b32_e32 v120, v93
	v_mov_b32_e32 v121, v93
	v_mov_b32_e32 v122, v93
	v_mov_b32_e32 v123, v93
	v_mov_b32_e32 v124, v93
	v_mov_b32_e32 v125, v93
	v_mov_b32_e32 v126, v93
	v_mov_b32_e32 v127, v93
	v_mov_b32_e32 v136, v93
	v_mov_b32_e32 v137, v93
	v_mov_b32_e32 v138, v93
	v_mov_b32_e32 v139, v93
	v_mov_b32_e32 v140, v93
	v_mov_b32_e32 v141, v93
	v_mov_b32_e32 v142, v93
	v_mov_b32_e32 v143, v93
	s_barrier

.LBB0_650:
	s_waitcnt lgkmcnt(0)
	s_barrier
	ds_read_b32 v0, v140
	s_waitcnt lgkmcnt(0)
	v_readfirstlane_b32 s16, v0
	s_cmp_eq_u32 s16, 0
	s_cbranch_scc1 .LBB0_657
	v_mbcnt_lo_u32_b32 v0, -1, 0
	v_mbcnt_hi_u32_b32 v0, -1, v0
	s_add_i32 s17, s16, -1
	v_add_u32_e32 v13, s94, v0
	s_ashr_i32 s16, s17, 2
	v_ashrrev_i32_e32 v1, 31, v13
	v_lshrrev_b32_e32 v1, 26, v1
	v_add_u32_e32 v1, v13, v1
	v_ashrrev_i32_e32 v8, 6, v1
	v_bfe_i32 v1, v13, 27, 1
	v_lshlrev_b32_e32 v0, 4, v13
	v_lshrrev_b32_e32 v1, 22, v1
	v_add_u32_e32 v1, v0, v1
	v_and_b32_e32 v1, 0xfffffc00, v1
	v_sub_u32_e32 v1, v0, v1
	v_lshrrev_b32_e32 v2, 4, v1
	v_bitop3_b32 v1, v2, v1, 32 bitop3:0x6c
	v_ashrrev_i32_e32 v3, 31, v1
	v_lshrrev_b32_e32 v3, 26, v3
	v_add_u32_e32 v3, v1, v3
	v_lshlrev_b32_e32 v2, 3, v8
	v_ashrrev_i32_e32 v9, 6, v3
	v_and_b32_e32 v3, 0xc0, v3
	v_and_b32_e32 v2, -16, v2
	v_sub_u32_e32 v1, v1, v3
	v_add_u32_e32 v2, v9, v2
	v_ashrrev_i16_sdwa v1, v141, sext(v1) dst_sel:DWORD dst_unused:UNUSED_PAD src0_sel:DWORD src1_sel:BYTE_0
	v_lshlrev_b32_e32 v4, 5, v8
	v_bfe_i32 v10, v1, 0, 16
	v_lshlrev_b32_e32 v1, 1, v2
	v_lshrrev_b32_e32 v3, 2, v2
	v_and_b32_e32 v5, 3, v9
	v_and_b32_e32 v4, 32, v4
	v_and_b32_e32 v1, 24, v1
	v_and_b32_e32 v3, 4, v3
	v_and_or_b32 v5, v2, s48, v5
	v_or3_b32 v1, v5, v3, v1
	v_add_lshl_u32 v3, v4, v10, 1
	v_add_u32_e32 v0, 0x2000, v0
	v_lshl_add_u32 v128, v1, 11, v3
	v_ashrrev_i32_e32 v1, 31, v0
	v_lshrrev_b32_e32 v1, 22, v1
	v_add_u32_e32 v1, v0, v1
	v_ashrrev_i32_e32 v11, 10, v1
	v_mul_i32_i24_e32 v1, 0x400, v11
	v_sub_u32_e32 v0, v0, v1
	v_lshrrev_b32_e32 v1, 4, v0
	v_bitop3_b32 v0, v1, v0, 32 bitop3:0x6c
	v_lshl_add_u32 v130, v2, 11, v3
	v_ashrrev_i32_e32 v2, 31, v0
	v_lshrrev_b32_e32 v2, 26, v2
	v_readfirstlane_b32 s45, v13
	v_add_u32_e32 v2, v0, v2
	s_and_b32 s44, s17, 3
	v_lshlrev_b32_e32 v1, 3, v11
	v_ashrrev_i32_e32 v12, 6, v2
	v_and_b32_e32 v2, 0xc0, v2
	s_ashr_i32 s42, s45, 6
	s_ashr_i32 s17, s16, 31
	s_ashr_i32 s40, s45, 8
	v_and_b32_e32 v1, -16, v1
	v_sub_u32_e32 v0, v0, v2
	s_lshl_b32 s46, s42, 10
	s_lshl_b64 s[34:35], s[16:17], 19
	s_lshl_b32 s41, s44, 19
	v_add_u32_e32 v1, v12, v1
	v_ashrrev_i16_sdwa v0, v141, sext(v0) dst_sel:DWORD dst_unused:UNUSED_PAD src0_sel:DWORD src1_sel:BYTE_0
	s_add_u32 s18, s25, s41
	v_lshlrev_b32_e32 v3, 5, v11
	v_bfe_i32 v14, v0, 0, 16
	v_lshlrev_b32_e32 v0, 1, v1
	v_lshrrev_b32_e32 v2, 2, v1
	v_and_b32_e32 v4, 3, v12
	s_addc_u32 s19, s27, 0
	s_add_i32 s17, s46, 0
	v_and_b32_e32 v3, 32, v3
	v_and_b32_e32 v0, 24, v0
	v_and_b32_e32 v2, 4, v2
	v_and_or_b32 v4, v1, s48, v4
	s_add_i32 m0, s17, 0x10000
	v_or3_b32 v0, v4, v2, v0
	v_add_lshl_u32 v2, v3, v14, 1
	global_load_lds_dwordx4 v128, s[18:19]
	s_add_i32 m0, s17, 0x12000
	v_lshl_add_u32 v134, v0, 11, v2
	s_add_u32 s22, s18, 0x40000
	global_load_lds_dwordx4 v134, s[18:19]
	s_addc_u32 s23, s19, 0
	s_add_i32 m0, s17, 0x14000
	v_lshl_add_u32 v132, v1, 11, v2
	global_load_lds_dwordx4 v128, s[22:23]
	s_add_i32 m0, s17, 0x16000
	v_mov_b32_e32 v135, v129
	global_load_lds_dwordx4 v134, s[22:23]
	s_add_u32 s22, s30, s34
	s_addc_u32 s23, s31, s35
	s_add_i32 s47, s17, 0x2000
	s_mov_b32 m0, s17
	s_add_u32 s56, s22, 0x40000
	global_load_lds_dwordx4 v130, s[22:23]
	s_mov_b32 m0, s47
	s_addc_u32 s57, s23, 0
	s_add_i32 s53, s17, 0x4000
	global_load_lds_dwordx4 v132, s[22:23]
	s_mov_b32 m0, s53
	s_add_i32 s54, s17, 0x6000
	global_load_lds_dwordx4 v130, s[56:57]
	s_mov_b32 m0, s54
	v_mov_b32_e32 v131, v129
	global_load_lds_dwordx4 v132, s[56:57]
	v_mov_b32_e32 v133, v129
	v_lshl_add_u64 v[6:7], s[18:19], 0, v[128:129]
	v_lshl_add_u64 v[4:5], s[18:19], 0, v[134:135]
	v_lshl_add_u64 v[2:3], s[22:23], 0, v[130:131]
	s_cmp_lg_u32 s40, 1
	s_cselect_b64 vcc, -1, 0
	v_lshl_add_u64 v[0:1], s[22:23], 0, v[132:133]
.LBB0_653:
	v_lshrrev_b32_e32 v16, 1, v13
	v_and_b32_e32 v143, 24, v16
	s_lshl_b32 s42, s42, 5
	v_and_b32_e32 v15, 15, v13
	v_lshlrev_b32_e32 v16, 1, v143
	v_lshlrev_b32_e32 v13, 2, v13
	s_and_b32 s55, s42, 0x60
	s_add_i32 m0, s17, 0x18000
	v_lshl_add_u64 v[6:7], v[6:7], 0, s[8:9]
	v_lshl_or_b32 v142, s40, 6, v15
	v_lshl_or_b32 v15, v15, 6, v16
	v_and_b32_e32 v13, 32, v13
	s_lshl_b32 s40, s40, 13
	s_lshl_b32 s42, s55, 7
	global_load_lds_dwordx4 v[6:7], off
	v_lshl_add_u64 v[4:5], v[4:5], 0, s[8:9]
	s_add_i32 m0, s17, 0x1a000
	s_add_i32 s56, s17, 0x8000
	s_add_i32 s57, s17, 0xa000
	v_bitop3_b32 v144, v15, s42, v13 bitop3:0xde
	global_load_lds_dwordx4 v[4:5], off
	v_lshl_add_u64 v[2:3], v[2:3], 0, s[8:9]
	s_mov_b32 m0, s56
	s_add_u32 s42, s18, 0x40080
	global_load_lds_dwordx4 v[2:3], off
	v_lshl_add_u64 v[0:1], v[0:1], 0, s[8:9]
	s_mov_b32 m0, s57
	s_addc_u32 s43, s19, 0
	global_load_lds_dwordx4 v[0:1], off
	s_add_i32 m0, s17, 0x1c000
	v_lshl_add_u64 v[0:1], s[42:43], 0, v[128:129]
	global_load_lds_dwordx4 v[0:1], off
	v_lshl_add_u64 v[0:1], s[42:43], 0, v[134:135]
	s_add_i32 m0, s17, 0x1e000
	s_add_u32 s58, s66, s34
	global_load_lds_dwordx4 v[0:1], off
	s_cbranch_vccnz .Lpro_skip2
	s_barrier
.Lpro_skip2:
	s_waitcnt vmcnt(8)
	s_barrier
	v_lshlrev_b32_e32 v0, 14, v8
	v_and_b32_e32 v0, 0xffff8000, v0
	s_addc_u32 s59, s67, s35
	v_lshl_add_u32 v0, v9, 11, v0
	v_and_b32_e32 v1, 1, v8
	v_lshl_or_b32 v0, v1, 6, v0
	s_add_u32 s34, s0, s34
	v_lshl_add_u32 v0, v10, 1, v0
	v_mov_b32_e32 v1, v129
	s_addc_u32 s35, s1, s35
	v_lshl_add_u64 v[136:137], s[34:35], 0, v[0:1]
	v_lshlrev_b32_e32 v0, 14, v11
	v_and_b32_e32 v0, 0xffff8000, v0
	v_lshl_add_u32 v0, v12, 11, v0
	v_and_b32_e32 v1, 1, v11
	v_lshl_or_b32 v0, v1, 6, v0
	s_waitcnt vmcnt(6)
	v_lshl_add_u32 v0, v14, 1, v0
	v_mov_b32_e32 v1, v129
	v_bitop3_b32 v13, v15, s40, v13 bitop3:0xde
	v_lshl_add_u64 v[138:139], s[34:35], 0, v[0:1]
	s_add_u32 s60, s24, s41
	v_mov_b32_e32 v0, 0
	s_addc_u32 s61, s26, 0
	s_mov_b32 s62, -2
	s_mov_b64 s[34:35], 0
	v_add_u32_e32 v145, 0, v13
	v_mov_b32_e32 v1, v0
	v_mov_b32_e32 v2, v0
	v_mov_b32_e32 v3, v0
	v_mov_b32_e32 v4, v0
	v_mov_b32_e32 v5, v0
	v_mov_b32_e32 v6, v0
	v_mov_b32_e32 v7, v0
	v_mov_b32_e32 v8, v0
	v_mov_b32_e32 v9, v0
	v_mov_b32_e32 v10, v0
	v_mov_b32_e32 v11, v0
	v_mov_b32_e32 v16, v0
	v_mov_b32_e32 v17, v0
	v_mov_b32_e32 v18, v0
	v_mov_b32_e32 v19, v0
	v_mov_b32_e32 v24, v0
	v_mov_b32_e32 v25, v0
	v_mov_b32_e32 v26, v0
	v_mov_b32_e32 v27, v0
	v_mov_b32_e32 v32, v0
	v_mov_b32_e32 v33, v0
	v_mov_b32_e32 v34, v0
	v_mov_b32_e32 v35, v0
	v_mov_b32_e32 v40, v0
	v_mov_b32_e32 v41, v0
	v_mov_b32_e32 v42, v0
	v_mov_b32_e32 v43, v0
	v_mov_b32_e32 v48, v0
	v_mov_b32_e32 v49, v0
	v_mov_b32_e32 v50, v0
	v_mov_b32_e32 v51, v0
	v_mov_b32_e32 v12, v0
	v_mov_b32_e32 v13, v0
	v_mov_b32_e32 v14, v0
	v_mov_b32_e32 v15, v0
	v_mov_b32_e32 v20, v0
	v_mov_b32_e32 v21, v0
	v_mov_b32_e32 v22, v0
	v_mov_b32_e32 v23, v0
	v_mov_b32_e32 v28, v0
	v_mov_b32_e32 v29, v0
	v_mov_b32_e32 v30, v0
	v_mov_b32_e32 v31, v0
	v_mov_b32_e32 v36, v0
	v_mov_b32_e32 v37, v0
	v_mov_b32_e32 v38, v0
	v_mov_b32_e32 v39, v0
	v_mov_b32_e32 v44, v0
	v_mov_b32_e32 v45, v0
	v_mov_b32_e32 v46, v0
	v_mov_b32_e32 v47, v0
	v_mov_b32_e32 v52, v0
	v_mov_b32_e32 v53, v0
	v_mov_b32_e32 v54, v0
	v_mov_b32_e32 v55, v0
	v_mov_b32_e32 v56, v0
	v_mov_b32_e32 v57, v0
	v_mov_b32_e32 v58, v0
	v_mov_b32_e32 v59, v0
	v_mov_b32_e32 v60, v0
	v_mov_b32_e32 v61, v0
	v_mov_b32_e32 v62, v0
	v_mov_b32_e32 v63, v0
	v_mov_b32_e32 v64, v0
	v_mov_b32_e32 v65, v0
	v_mov_b32_e32 v66, v0
	v_mov_b32_e32 v67, v0
	v_mov_b32_e32 v68, v0
	v_mov_b32_e32 v69, v0
	v_mov_b32_e32 v70, v0
	v_mov_b32_e32 v71, v0
	v_mov_b32_e32 v72, v0
	v_mov_b32_e32 v73, v0
	v_mov_b32_e32 v74, v0
	v_mov_b32_e32 v75, v0
	v_mov_b32_e32 v80, v0
	v_mov_b32_e32 v81, v0
	v_mov_b32_e32 v82, v0
	v_mov_b32_e32 v83, v0
	v_mov_b32_e32 v88, v0
	v_mov_b32_e32 v89, v0
	v_mov_b32_e32 v90, v0
	v_mov_b32_e32 v91, v0
	v_mov_b32_e32 v96, v0
	v_mov_b32_e32 v97, v0
	v_mov_b32_e32 v98, v0
	v_mov_b32_e32 v99, v0
	v_mov_b32_e32 v104, v0
	v_mov_b32_e32 v105, v0
	v_mov_b32_e32 v106, v0
	v_mov_b32_e32 v107, v0
	v_mov_b32_e32 v112, v0
	v_mov_b32_e32 v113, v0
	v_mov_b32_e32 v114, v0
	v_mov_b32_e32 v115, v0
	v_mov_b32_e32 v76, v0
	v_mov_b32_e32 v77, v0
	v_mov_b32_e32 v78, v0
	v_mov_b32_e32 v79, v0
	v_mov_b32_e32 v84, v0
	v_mov_b32_e32 v85, v0
	v_mov_b32_e32 v86, v0
	v_mov_b32_e32 v87, v0
	v_mov_b32_e32 v92, v0
	v_mov_b32_e32 v93, v0
	v_mov_b32_e32 v94, v0
	v_mov_b32_e32 v95, v0
	v_mov_b32_e32 v100, v0
	v_mov_b32_e32 v101, v0
	v_mov_b32_e32 v102, v0
	v_mov_b32_e32 v103, v0
	v_mov_b32_e32 v108, v0
	v_mov_b32_e32 v109, v0
	v_mov_b32_e32 v110, v0
	v_mov_b32_e32 v111, v0
	v_mov_b32_e32 v116, v0
	v_mov_b32_e32 v117, v0
	v_mov_b32_e32 v118, v0
	v_mov_b32_e32 v119, v0
	v_mov_b32_e32 v120, v0
	v_mov_b32_e32 v121, v0
	v_mov_b32_e32 v122, v0
	v_mov_b32_e32 v123, v0
	v_mov_b32_e32 v124, v0
	v_mov_b32_e32 v125, v0
	v_mov_b32_e32 v126, v0
	v_mov_b32_e32 v127, v0
	s_barrier

.LBB0_719:
	v_lshlrev_b32_e32 v0, 4, v150
	v_add_u32_e32 v1, 0x2000, v0
	v_ashrrev_i32_e32 v2, 31, v1
	v_lshrrev_b32_e32 v2, 22, v2
	v_add_u32_e32 v2, v1, v2
	v_ashrrev_i32_e32 v2, 10, v2
	v_mul_i32_i24_e32 v3, 0x400, v2
	v_sub_u32_e32 v1, v1, v3
	v_lshrrev_b32_e32 v3, 4, v1
	v_bitop3_b32 v1, v3, v1, 32 bitop3:0x6c
	v_readlane_b32 s2, v247, 11
	v_ashrrev_i32_e32 v3, 31, v1
	s_and_b32 s15, s2, 3
	s_ashr_i32 s7, s0, 6
	s_ashr_i32 s14, s2, 4
	v_lshrrev_b32_e32 v3, 26, v3
	s_ashr_i32 s8, s0, 8
	s_lshl_b32 s6, s7, 10
	s_bfe_u32 s1, s2, 0x20002
	s_add_i32 s4, s14, 64
	s_lshl_b32 s2, s15, 9
	v_add_u32_e32 v3, v1, v3
	v_lshlrev_b32_e32 v5, 3, v2
	s_add_u32 s3, s25, s2
	v_ashrrev_i32_e32 v4, 6, v3
	v_and_b32_e32 v5, -16, v5
	v_and_b32_e32 v3, 0xc0, v3
	s_addc_u32 s9, s27, 0
	v_add_u32_e32 v5, v4, v5
	v_sub_u32_e32 v1, v1, v3
	v_mov_b32_e32 v3, 1
	s_add_u32 s16, s30, s2
	v_and_b32_e32 v4, 3, v4
	s_mov_b32 s2, 0x1fffe0
	v_lshrrev_b32_e32 v6, 2, v5
	v_lshlrev_b32_e32 v7, 1, v5
	v_lshlrev_b32_e32 v2, 5, v2
	v_ashrrev_i16_sdwa v1, v3, sext(v1) dst_sel:DWORD dst_unused:UNUSED_PAD src0_sel:DWORD src1_sel:BYTE_0
	v_and_or_b32 v4, v5, s2, v4
	v_and_b32_e32 v6, 4, v6
	v_and_b32_e32 v7, 24, v7
	v_and_b32_e32 v2, 32, v2
	v_bfe_i32 v1, v1, 0, 16
	v_or3_b32 v4, v4, v6, v7
	v_add_lshl_u32 v1, v2, v1, 1
	v_lshl_add_u32 v20, v4, 11, v1
	v_lshl_add_u32 v4, v5, 11, v1
	v_bfe_i32 v1, v150, 27, 1
	v_lshrrev_b32_e32 v1, 22, v1
	v_add_u32_e32 v1, v0, v1
	v_and_b32_e32 v1, 0xfffffc00, v1
	v_sub_u32_e32 v0, v0, v1
	v_lshrrev_b32_e32 v1, 4, v0
	v_ashrrev_i32_e32 v5, 31, v150
	v_bitop3_b32 v0, v1, v0, 32 bitop3:0x6c
	v_lshrrev_b32_e32 v5, 26, v5
	v_ashrrev_i32_e32 v1, 31, v0
	v_add_u32_e32 v5, v150, v5
	v_lshrrev_b32_e32 v1, 26, v1
	v_ashrrev_i32_e32 v5, 6, v5
	v_add_u32_e32 v1, v0, v1
	v_lshlrev_b32_e32 v6, 3, v5
	v_ashrrev_i32_e32 v2, 6, v1
	v_and_b32_e32 v6, -16, v6
	v_and_b32_e32 v1, 0xc0, v1
	s_addc_u32 s17, s31, 0
	v_add_u32_e32 v6, v2, v6
	v_and_b32_e32 v2, 3, v2
	v_sub_u32_e32 v0, v0, v1
	s_ashr_i32 s5, s4, 31
	v_and_or_b32 v2, v6, s2, v2
	v_lshrrev_b32_e32 v7, 2, v6
	v_lshlrev_b32_e32 v8, 1, v6
	v_lshlrev_b32_e32 v5, 5, v5
	v_ashrrev_i16_sdwa v0, v3, sext(v0) dst_sel:DWORD dst_unused:UNUSED_PAD src0_sel:DWORD src1_sel:BYTE_0
	s_lshl_b64 s[10:11], s[4:5], 19
	s_lshl_b32 s2, s1, 19
	v_and_b32_e32 v7, 4, v7
	v_and_b32_e32 v8, 24, v8
	v_and_b32_e32 v5, 32, v5
	v_bfe_i32 v0, v0, 0, 16
	s_add_u32 s2, s3, s2
	v_or3_b32 v2, v2, v7, v8
	v_add_lshl_u32 v0, v5, v0, 1
	s_addc_u32 s3, s9, 0
	s_add_i32 s27, s6, 0
	v_lshl_add_u32 v22, v2, 11, v0
	s_add_i32 m0, s27, 0x10000
	v_lshl_add_u32 v6, v6, 11, v0
	global_load_lds_dwordx4 v22, s[2:3]
	s_add_i32 m0, s27, 0x12000
	s_add_u32 s12, s2, 0x40000
	global_load_lds_dwordx4 v20, s[2:3]
	s_addc_u32 s13, s3, 0
	s_add_i32 m0, s27, 0x14000
	v_mov_b32_e32 v23, 0
	global_load_lds_dwordx4 v22, s[12:13]
	s_add_i32 m0, s27, 0x16000
	s_add_u32 s10, s16, s10
	s_addc_u32 s11, s17, s11
	s_add_i32 s28, s27, 0x2000
	global_load_lds_dwordx4 v20, s[12:13]
	s_mov_b32 m0, s27
	s_add_u32 s16, s10, 0x40000
	global_load_lds_dwordx4 v6, s[10:11]
	s_mov_b32 m0, s28
	s_addc_u32 s17, s11, 0
	s_add_i32 s23, s27, 0x4000
	global_load_lds_dwordx4 v4, s[10:11]
	s_mov_b32 m0, s23
	s_add_i32 s24, s27, 0x6000
	global_load_lds_dwordx4 v6, s[16:17]
	s_mov_b32 m0, s24
	v_mov_b32_e32 v21, v23
	global_load_lds_dwordx4 v4, s[16:17]
	v_mov_b32_e32 v7, v23
	v_mov_b32_e32 v5, v23
	v_lshl_add_u64 v[16:17], s[2:3], 0, v[22:23]
	v_lshl_add_u64 v[18:19], s[2:3], 0, v[20:21]
	v_lshl_add_u64 v[14:15], s[12:13], 0, v[22:23]
	v_lshl_add_u64 v[8:9], s[12:13], 0, v[20:21]
	v_lshl_add_u64 v[10:11], s[10:11], 0, v[6:7]
	v_lshl_add_u64 v[12:13], s[10:11], 0, v[4:5]
	v_lshl_add_u64 v[0:1], s[16:17], 0, v[6:7]
	s_cmp_lg_u32 s8, 1
	s_cselect_b64 vcc, -1, 0
	v_lshl_add_u64 v[2:3], s[16:17], 0, v[4:5]
.LBB0_721:
	s_lshl_b32 s7, s7, 5
	s_add_i32 s13, 0, 0x18000
	s_lshl_b32 s5, s8, 6
	s_lshl_b32 s12, s8, 13
	s_and_b32 s16, s7, 0x60
	s_add_i32 s17, s13, s6
	s_mov_b64 s[8:9], 0x80
	s_lshl_b32 s7, s16, 7
	v_lshl_add_u64 v[30:31], v[16:17], 0, s[8:9]
	s_mov_b32 m0, s17
	s_add_i32 s19, s17, 0x2000
	s_add_i32 s18, s27, 0x8000
	s_add_i32 s22, s27, 0xa000
	global_load_lds_dwordx4 v[30:31], off
	v_lshl_add_u64 v[36:37], v[18:19], 0, s[8:9]
	s_mov_b32 m0, s19
	v_lshl_add_u64 v[28:29], v[10:11], 0, s[8:9]
	v_lshl_add_u64 v[38:39], v[12:13], 0, s[8:9]
	s_add_u32 s8, s2, 0x40080
	global_load_lds_dwordx4 v[36:37], off
	s_mov_b32 m0, s18
	s_addc_u32 s9, s3, 0
	s_add_i32 s29, 0, 0x1c000
	global_load_lds_dwordx4 v[28:29], off
	s_mov_b32 m0, s22
	s_add_i32 s25, s29, s6
	global_load_lds_dwordx4 v[38:39], off
	v_lshl_add_u64 v[52:53], s[8:9], 0, v[22:23]
	s_mov_b32 m0, s25
	s_add_i32 s26, s25, 0x2000
	global_load_lds_dwordx4 v[52:53], off
	v_lshl_add_u64 v[54:55], s[8:9], 0, v[20:21]
	s_mov_b32 m0, s26
	v_lshrrev_b32_e32 v24, 1, v150
	global_load_lds_dwordx4 v[54:55], off
	s_cbranch_vccnz .Lpro_skip3
	s_barrier
.Lpro_skip3:
	s_waitcnt vmcnt(8)
	s_barrier
	v_and_b32_e32 v129, 24, v24
	v_and_b32_e32 v128, 15, v150
	v_lshlrev_b32_e32 v24, 1, v129
	v_lshlrev_b32_e32 v25, 2, v150
	v_lshl_or_b32 v24, v128, 6, v24
	v_and_b32_e32 v25, 32, v25
	v_bitop3_b32 v26, v24, s12, v25 bitop3:0xde
	v_bitop3_b32 v24, v24, s7, v25 bitop3:0xde
	s_add_i32 s30, 0, 0x10000
	s_add_i32 s33, 0, 0x14000
	v_add_u32_e32 v232, s30, v24
	s_add_u32 s36, s10, 0x40080
	s_waitcnt vmcnt(6)
	s_barrier
	v_add_u32_e32 v233, s33, v24
	v_add_u32_e32 v246, 0, v26
	v_add_u32_e32 v234, s13, v24
	v_add_u32_e32 v235, s29, v24
	s_addc_u32 s37, s11, 0
	s_add_i32 s30, s30, s6
	ds_read_b128 v[24:27], v232
	ds_read_b128 v[32:35], v232 offset:1024
	ds_read_b128 v[40:43], v232 offset:2048
	ds_read_b128 v[44:47], v232 offset:3072
	ds_read_b128 v[48:51], v233
	ds_read_b128 v[56:59], v233 offset:1024
	ds_read_b128 v[60:63], v233 offset:2048
	ds_read_b128 v[64:67], v233 offset:3072
	s_add_i32 s35, s27, 0xc000
	s_add_i32 s34, s27, 0xe000
	s_add_i32 s29, s30, 0x2000
	s_add_u32 s12, s2, 0x40100
	s_addc_u32 s13, s3, 0
	s_add_i32 s33, s33, s6
	s_add_i32 s31, s33, 0x2000
	s_add_u32 s8, s10, 0x40100
	s_addc_u32 s9, s11, 0
	s_add_u32 s6, s2, 0x40180
	s_addc_u32 s7, s3, 0
	s_add_u32 s2, s10, 0x40180
	s_addc_u32 s3, s11, 0
	s_cmpk_gt_u32 s0, 0xff
	s_mov_b32 m0, s35
	v_lshl_add_u64 v[100:101], s[36:37], 0, v[6:7]
	ds_read_b128 v[68:71], v246
	ds_read_b128 v[72:75], v246 offset:1024
	ds_read_b128 v[76:79], v246 offset:2048
	ds_read_b128 v[80:83], v246 offset:3072
	ds_read_b128 v[84:87], v246 offset:4096
	ds_read_b128 v[88:91], v246 offset:5120
	ds_read_b128 v[92:95], v246 offset:6144
	ds_read_b128 v[96:99], v246 offset:7168
	global_load_lds_dwordx4 v[100:101], off
	v_lshl_add_u64 v[100:101], s[36:37], 0, v[4:5]
	s_mov_b32 m0, s34
	s_nop 0
	global_load_lds_dwordx4 v[100:101], off
	s_waitcnt vmcnt(8)
	s_waitcnt lgkmcnt(0)
	s_barrier
	s_setprio 1
	s_waitcnt lgkmcnt(0)
	v_mfma_f32_16x16x32_bf16 v[100:103], v[24:27], v[68:71], 0
	v_mfma_f32_16x16x32_bf16 v[104:107], v[40:43], v[68:71], 0
	v_mfma_f32_16x16x32_bf16 v[108:111], v[24:27], v[76:79], 0
	v_mfma_f32_16x16x32_bf16 v[112:115], v[40:43], v[76:79], 0
	v_mfma_f32_16x16x32_bf16 v[116:119], v[24:27], v[84:87], 0
	v_mfma_f32_16x16x32_bf16 v[120:123], v[40:43], v[84:87], 0
	v_mfma_f32_16x16x32_bf16 v[124:127], v[24:27], v[92:95], 0
	v_mfma_f32_16x16x32_bf16 v[100:103], v[32:35], v[72:75], v[100:103]
	v_mfma_f32_16x16x32_bf16 v[104:107], v[44:47], v[72:75], v[104:107]
	v_mfma_f32_16x16x32_bf16 v[108:111], v[32:35], v[80:83], v[108:111]
	v_mfma_f32_16x16x32_bf16 v[112:115], v[44:47], v[80:83], v[112:115]
	v_mfma_f32_16x16x32_bf16 v[116:119], v[32:35], v[88:91], v[116:119]
	v_mfma_f32_16x16x32_bf16 v[120:123], v[44:47], v[88:91], v[120:123]
	v_mfma_f32_16x16x32_bf16 v[124:127], v[32:35], v[96:99], v[124:127]
	v_mfma_f32_16x16x32_bf16 v[130:133], v[40:43], v[92:95], 0
	v_mfma_f32_16x16x32_bf16 v[130:133], v[44:47], v[96:99], v[130:133]
	s_setprio 0
	s_setprio 1
	v_mfma_f32_16x16x32_bf16 v[134:137], v[48:51], v[68:71], 0
	v_mfma_f32_16x16x32_bf16 v[68:71], v[60:63], v[68:71], 0
	v_mfma_f32_16x16x32_bf16 v[134:137], v[56:59], v[72:75], v[134:137]
	v_mfma_f32_16x16x32_bf16 v[68:71], v[64:67], v[72:75], v[68:71]
	v_mfma_f32_16x16x32_bf16 v[72:75], v[48:51], v[76:79], 0
	v_mfma_f32_16x16x32_bf16 v[76:79], v[60:63], v[76:79], 0
	v_mfma_f32_16x16x32_bf16 v[72:75], v[56:59], v[80:83], v[72:75]
	v_mfma_f32_16x16x32_bf16 v[76:79], v[64:67], v[80:83], v[76:79]
	v_mfma_f32_16x16x32_bf16 v[80:83], v[48:51], v[84:87], 0
	v_mfma_f32_16x16x32_bf16 v[84:87], v[60:63], v[84:87], 0
	v_mfma_f32_16x16x32_bf16 v[80:83], v[56:59], v[88:91], v[80:83]
	v_mfma_f32_16x16x32_bf16 v[84:87], v[64:67], v[88:91], v[84:87]
	v_mfma_f32_16x16x32_bf16 v[88:91], v[48:51], v[92:95], 0
	v_mfma_f32_16x16x32_bf16 v[92:95], v[60:63], v[92:95], 0
	v_mfma_f32_16x16x32_bf16 v[88:91], v[56:59], v[96:99], v[88:91]
	v_mfma_f32_16x16x32_bf16 v[92:95], v[64:67], v[96:99], v[92:95]
	s_setprio 0
	s_barrier
	s_mov_b64 s[10:11], 0x100
	s_mov_b32 m0, s30
	v_lshl_add_u64 v[166:167], v[16:17], 0, s[10:11]
	ds_read_b128 v[96:99], v246 offset:16384
	ds_read_b128 v[138:141], v246 offset:17408
	ds_read_b128 v[142:145], v246 offset:18432
	ds_read_b128 v[146:149], v246 offset:19456
	ds_read_b128 v[150:153], v246 offset:20480
	ds_read_b128 v[154:157], v246 offset:21504
	ds_read_b128 v[158:161], v246 offset:22528
	ds_read_b128 v[162:165], v246 offset:23552
	global_load_lds_dwordx4 v[166:167], off
	v_lshl_add_u64 v[166:167], v[18:19], 0, s[10:11]
	s_mov_b32 m0, s29
	s_nop 0
	global_load_lds_dwordx4 v[166:167], off
	v_lshl_add_u64 v[166:167], s[12:13], 0, v[22:23]
	s_mov_b32 m0, s33
	s_nop 0
	global_load_lds_dwordx4 v[166:167], off
	v_lshl_add_u64 v[166:167], s[12:13], 0, v[20:21]
	s_mov_b32 m0, s31
	s_nop 0
	global_load_lds_dwordx4 v[166:167], off
	v_lshl_add_u64 v[166:167], v[10:11], 0, s[10:11]
	s_mov_b32 m0, s27
	s_nop 0
	global_load_lds_dwordx4 v[166:167], off
	v_lshl_add_u64 v[166:167], v[12:13], 0, s[10:11]
	s_mov_b32 m0, s28
	s_nop 0
	global_load_lds_dwordx4 v[166:167], off
	s_waitcnt vmcnt(8)
	s_waitcnt lgkmcnt(0)
	s_barrier
	s_setprio 1
	s_waitcnt lgkmcnt(0)
	v_mfma_f32_16x16x32_bf16 v[166:169], v[24:27], v[96:99], 0
	v_mfma_f32_16x16x32_bf16 v[174:177], v[24:27], v[142:145], 0
	v_mfma_f32_16x16x32_bf16 v[182:185], v[24:27], v[150:153], 0
	v_mfma_f32_16x16x32_bf16 v[24:27], v[24:27], v[158:161], 0
	v_mfma_f32_16x16x32_bf16 v[166:169], v[32:35], v[138:141], v[166:169]
	v_mfma_f32_16x16x32_bf16 v[174:177], v[32:35], v[146:149], v[174:177]
	v_mfma_f32_16x16x32_bf16 v[182:185], v[32:35], v[154:157], v[182:185]
	v_mfma_f32_16x16x32_bf16 v[24:27], v[32:35], v[162:165], v[24:27]
	v_mfma_f32_16x16x32_bf16 v[32:35], v[40:43], v[158:161], 0
	v_mfma_f32_16x16x32_bf16 v[170:173], v[40:43], v[96:99], 0
	v_mfma_f32_16x16x32_bf16 v[178:181], v[40:43], v[142:145], 0
	v_mfma_f32_16x16x32_bf16 v[186:189], v[40:43], v[150:153], 0
	v_mfma_f32_16x16x32_bf16 v[32:35], v[44:47], v[162:165], v[32:35]
	v_mfma_f32_16x16x32_bf16 v[170:173], v[44:47], v[138:141], v[170:173]
	v_mfma_f32_16x16x32_bf16 v[178:181], v[44:47], v[146:149], v[178:181]
	v_mfma_f32_16x16x32_bf16 v[186:189], v[44:47], v[154:157], v[186:189]
	s_setprio 0
	s_setprio 1
	v_mfma_f32_16x16x32_bf16 v[40:43], v[48:51], v[96:99], 0
	v_mfma_f32_16x16x32_bf16 v[44:47], v[60:63], v[96:99], 0
	v_mfma_f32_16x16x32_bf16 v[40:43], v[56:59], v[138:141], v[40:43]
	v_mfma_f32_16x16x32_bf16 v[44:47], v[64:67], v[138:141], v[44:47]
	v_mfma_f32_16x16x32_bf16 v[96:99], v[48:51], v[142:145], 0
	v_mfma_f32_16x16x32_bf16 v[138:141], v[60:63], v[142:145], 0
	v_mfma_f32_16x16x32_bf16 v[142:145], v[48:51], v[150:153], 0
	v_mfma_f32_16x16x32_bf16 v[48:51], v[48:51], v[158:161], 0
	v_mfma_f32_16x16x32_bf16 v[96:99], v[56:59], v[146:149], v[96:99]
	v_mfma_f32_16x16x32_bf16 v[142:145], v[56:59], v[154:157], v[142:145]
	v_mfma_f32_16x16x32_bf16 v[48:51], v[56:59], v[162:165], v[48:51]
	v_mfma_f32_16x16x32_bf16 v[56:59], v[60:63], v[158:161], 0
	v_mfma_f32_16x16x32_bf16 v[138:141], v[64:67], v[146:149], v[138:141]
	v_mfma_f32_16x16x32_bf16 v[146:149], v[60:63], v[150:153], 0
	v_mfma_f32_16x16x32_bf16 v[56:59], v[64:67], v[162:165], v[56:59]
	v_mfma_f32_16x16x32_bf16 v[146:149], v[64:67], v[154:157], v[146:149]
	s_setprio 0
	s_barrier
	ds_read_b128 v[60:63], v234
	ds_read_b128 v[64:67], v234 offset:1024
	ds_read_b128 v[150:153], v234 offset:2048
	ds_read_b128 v[154:157], v234 offset:3072
	ds_read_b128 v[158:161], v235
	ds_read_b128 v[162:165], v235 offset:1024
	ds_read_b128 v[190:193], v235 offset:2048
	ds_read_b128 v[194:197], v235 offset:3072
	s_mov_b32 m0, s23
	v_lshl_add_u64 v[230:231], s[8:9], 0, v[6:7]
	ds_read_b128 v[198:201], v246 offset:32768
	ds_read_b128 v[202:205], v246 offset:33792
	ds_read_b128 v[206:209], v246 offset:34816
	ds_read_b128 v[210:213], v246 offset:35840
	ds_read_b128 v[214:217], v246 offset:36864
	ds_read_b128 v[218:221], v246 offset:37888
	ds_read_b128 v[222:225], v246 offset:38912
	ds_read_b128 v[226:229], v246 offset:39936
	global_load_lds_dwordx4 v[230:231], off
	v_lshl_add_u64 v[230:231], s[8:9], 0, v[4:5]
	s_mov_b32 m0, s24
	s_nop 0
	global_load_lds_dwordx4 v[230:231], off
	s_waitcnt vmcnt(8)
	s_waitcnt lgkmcnt(0)
	s_barrier
	s_setprio 1
	s_waitcnt lgkmcnt(0)
	v_mfma_f32_16x16x32_bf16 v[100:103], v[60:63], v[198:201], v[100:103]
	v_mfma_f32_16x16x32_bf16 v[104:107], v[150:153], v[198:201], v[104:107]
	v_mfma_f32_16x16x32_bf16 v[108:111], v[60:63], v[206:209], v[108:111]
	v_mfma_f32_16x16x32_bf16 v[112:115], v[150:153], v[206:209], v[112:115]
	v_mfma_f32_16x16x32_bf16 v[116:119], v[60:63], v[214:217], v[116:119]
	v_mfma_f32_16x16x32_bf16 v[120:123], v[150:153], v[214:217], v[120:123]
	v_mfma_f32_16x16x32_bf16 v[124:127], v[60:63], v[222:225], v[124:127]
	v_mfma_f32_16x16x32_bf16 v[100:103], v[64:67], v[202:205], v[100:103]
	v_mfma_f32_16x16x32_bf16 v[104:107], v[154:157], v[202:205], v[104:107]
	v_mfma_f32_16x16x32_bf16 v[108:111], v[64:67], v[210:213], v[108:111]
	v_mfma_f32_16x16x32_bf16 v[112:115], v[154:157], v[210:213], v[112:115]
	v_mfma_f32_16x16x32_bf16 v[116:119], v[64:67], v[218:221], v[116:119]
	v_mfma_f32_16x16x32_bf16 v[120:123], v[154:157], v[218:221], v[120:123]
	v_mfma_f32_16x16x32_bf16 v[124:127], v[64:67], v[226:229], v[124:127]
	v_mfma_f32_16x16x32_bf16 v[130:133], v[150:153], v[222:225], v[130:133]
	v_mfma_f32_16x16x32_bf16 v[130:133], v[154:157], v[226:229], v[130:133]
	s_setprio 0
	s_setprio 1
	v_mfma_f32_16x16x32_bf16 v[68:71], v[190:193], v[198:201], v[68:71]
	v_mfma_f32_16x16x32_bf16 v[72:75], v[158:161], v[206:209], v[72:75]
	v_mfma_f32_16x16x32_bf16 v[76:79], v[190:193], v[206:209], v[76:79]
	v_mfma_f32_16x16x32_bf16 v[80:83], v[158:161], v[214:217], v[80:83]
	v_mfma_f32_16x16x32_bf16 v[84:87], v[190:193], v[214:217], v[84:87]
	v_mfma_f32_16x16x32_bf16 v[88:91], v[158:161], v[222:225], v[88:91]
	v_mfma_f32_16x16x32_bf16 v[92:95], v[190:193], v[222:225], v[92:95]
	v_mfma_f32_16x16x32_bf16 v[134:137], v[158:161], v[198:201], v[134:137]
	v_mfma_f32_16x16x32_bf16 v[68:71], v[194:197], v[202:205], v[68:71]
	v_mfma_f32_16x16x32_bf16 v[72:75], v[162:165], v[210:213], v[72:75]
	v_mfma_f32_16x16x32_bf16 v[76:79], v[194:197], v[210:213], v[76:79]
	v_mfma_f32_16x16x32_bf16 v[80:83], v[162:165], v[218:221], v[80:83]
	v_mfma_f32_16x16x32_bf16 v[84:87], v[194:197], v[218:221], v[84:87]
	v_mfma_f32_16x16x32_bf16 v[88:91], v[162:165], v[226:229], v[88:91]
	v_mfma_f32_16x16x32_bf16 v[92:95], v[194:197], v[226:229], v[92:95]
	v_mfma_f32_16x16x32_bf16 v[134:137], v[162:165], v[202:205], v[134:137]
	s_setprio 0
	s_barrier
	s_mov_b64 s[8:9], 0x180
	s_mov_b32 m0, s17
	v_lshl_add_u64 v[230:231], v[16:17], 0, s[8:9]
	ds_read_b128 v[198:201], v246 offset:49152
	ds_read_b128 v[202:205], v246 offset:50176
	ds_read_b128 v[206:209], v246 offset:51200
	ds_read_b128 v[210:213], v246 offset:52224
	ds_read_b128 v[214:217], v246 offset:53248
	ds_read_b128 v[218:221], v246 offset:54272
	ds_read_b128 v[222:225], v246 offset:55296
	ds_read_b128 v[226:229], v246 offset:56320
	global_load_lds_dwordx4 v[230:231], off
	v_lshl_add_u64 v[230:231], v[18:19], 0, s[8:9]
	s_mov_b32 m0, s19
	v_lshl_add_u64 v[22:23], s[6:7], 0, v[22:23]
	global_load_lds_dwordx4 v[230:231], off
	s_mov_b32 m0, s25
	v_lshl_add_u64 v[20:21], s[6:7], 0, v[20:21]
	global_load_lds_dwordx4 v[22:23], off
	s_mov_b32 m0, s26
	s_nop 0
	global_load_lds_dwordx4 v[20:21], off
	v_lshl_add_u64 v[20:21], v[10:11], 0, s[8:9]
	s_mov_b32 m0, s18
	s_nop 0
	global_load_lds_dwordx4 v[20:21], off
	v_lshl_add_u64 v[20:21], v[12:13], 0, s[8:9]
	s_mov_b32 m0, s22
	s_nop 0
	global_load_lds_dwordx4 v[20:21], off
	s_waitcnt vmcnt(8)
	s_waitcnt lgkmcnt(0)
	s_barrier
	s_setprio 1
	s_waitcnt lgkmcnt(0)
	v_mfma_f32_16x16x32_bf16 v[20:23], v[60:63], v[198:201], v[166:169]
	v_mfma_f32_16x16x32_bf16 v[24:27], v[60:63], v[222:225], v[24:27]
	v_mfma_f32_16x16x32_bf16 v[32:35], v[150:153], v[222:225], v[32:35]
	v_mfma_f32_16x16x32_bf16 v[20:23], v[64:67], v[202:205], v[20:23]
	v_mfma_f32_16x16x32_bf16 v[166:169], v[150:153], v[198:201], v[170:173]
	v_mfma_f32_16x16x32_bf16 v[170:173], v[60:63], v[206:209], v[174:177]
	v_mfma_f32_16x16x32_bf16 v[174:177], v[150:153], v[206:209], v[178:181]
	v_mfma_f32_16x16x32_bf16 v[178:181], v[60:63], v[214:217], v[182:185]
	v_mfma_f32_16x16x32_bf16 v[182:185], v[150:153], v[214:217], v[186:189]
	v_mfma_f32_16x16x32_bf16 v[24:27], v[64:67], v[226:229], v[24:27]
	v_mfma_f32_16x16x32_bf16 v[32:35], v[154:157], v[226:229], v[32:35]
	v_mfma_f32_16x16x32_bf16 v[166:169], v[154:157], v[202:205], v[166:169]
	v_mfma_f32_16x16x32_bf16 v[170:173], v[64:67], v[210:213], v[170:173]
	v_mfma_f32_16x16x32_bf16 v[174:177], v[154:157], v[210:213], v[174:177]
	v_mfma_f32_16x16x32_bf16 v[178:181], v[64:67], v[218:221], v[178:181]
	v_mfma_f32_16x16x32_bf16 v[182:185], v[154:157], v[218:221], v[182:185]
	s_setprio 0
	s_setprio 1
	v_mfma_f32_16x16x32_bf16 v[40:43], v[158:161], v[198:201], v[40:43]
	v_mfma_f32_16x16x32_bf16 v[44:47], v[190:193], v[198:201], v[44:47]
	v_mfma_f32_16x16x32_bf16 v[60:63], v[158:161], v[206:209], v[96:99]
	v_mfma_f32_16x16x32_bf16 v[64:67], v[190:193], v[206:209], v[138:141]
	v_mfma_f32_16x16x32_bf16 v[96:99], v[158:161], v[214:217], v[142:145]
	v_mfma_f32_16x16x32_bf16 v[48:51], v[158:161], v[222:225], v[48:51]
	v_mfma_f32_16x16x32_bf16 v[56:59], v[190:193], v[222:225], v[56:59]
	v_mfma_f32_16x16x32_bf16 v[40:43], v[162:165], v[202:205], v[40:43]
	v_mfma_f32_16x16x32_bf16 v[44:47], v[194:197], v[202:205], v[44:47]
	v_mfma_f32_16x16x32_bf16 v[60:63], v[162:165], v[210:213], v[60:63]
	v_mfma_f32_16x16x32_bf16 v[64:67], v[194:197], v[210:213], v[64:67]
	v_mfma_f32_16x16x32_bf16 v[96:99], v[162:165], v[218:221], v[96:99]
	v_mfma_f32_16x16x32_bf16 v[138:141], v[190:193], v[214:217], v[146:149]
	v_mfma_f32_16x16x32_bf16 v[48:51], v[162:165], v[226:229], v[48:51]
	v_mfma_f32_16x16x32_bf16 v[56:59], v[194:197], v[226:229], v[56:59]
	v_mfma_f32_16x16x32_bf16 v[138:141], v[194:197], v[218:221], v[138:141]
	s_setprio 0
	s_barrier
	ds_read_b128 v[142:145], v232
	ds_read_b128 v[146:149], v232 offset:1024
	ds_read_b128 v[150:153], v232 offset:2048
	ds_read_b128 v[154:157], v232 offset:3072
	ds_read_b128 v[158:161], v233
	ds_read_b128 v[162:165], v233 offset:1024
	ds_read_b128 v[186:189], v233 offset:2048
	ds_read_b128 v[190:193], v233 offset:3072
	s_mov_b32 m0, s35
	v_lshl_add_u64 v[6:7], s[2:3], 0, v[6:7]
	ds_read_b128 v[194:197], v246
	ds_read_b128 v[198:201], v246 offset:1024
	ds_read_b128 v[202:205], v246 offset:2048
	ds_read_b128 v[206:209], v246 offset:3072
	ds_read_b128 v[210:213], v246 offset:4096
	ds_read_b128 v[214:217], v246 offset:5120
	ds_read_b128 v[218:221], v246 offset:6144
	ds_read_b128 v[222:225], v246 offset:7168
	global_load_lds_dwordx4 v[6:7], off
	v_lshl_add_u64 v[4:5], s[2:3], 0, v[4:5]
	s_mov_b32 m0, s34
	s_nop 0
	global_load_lds_dwordx4 v[4:5], off
	s_waitcnt vmcnt(8)
	s_waitcnt lgkmcnt(0)
	s_barrier
	s_setprio 1
	s_waitcnt lgkmcnt(0)
	v_mfma_f32_16x16x32_bf16 v[4:7], v[142:145], v[194:197], v[100:103]
	v_mfma_f32_16x16x32_bf16 v[100:103], v[150:153], v[194:197], v[104:107]
	v_mfma_f32_16x16x32_bf16 v[104:107], v[142:145], v[202:205], v[108:111]
	v_mfma_f32_16x16x32_bf16 v[108:111], v[150:153], v[202:205], v[112:115]
	v_mfma_f32_16x16x32_bf16 v[112:115], v[142:145], v[210:213], v[116:119]
	v_mfma_f32_16x16x32_bf16 v[116:119], v[150:153], v[210:213], v[120:123]
	v_mfma_f32_16x16x32_bf16 v[120:123], v[142:145], v[218:221], v[124:127]
	v_mfma_f32_16x16x32_bf16 v[124:127], v[150:153], v[218:221], v[130:133]
	v_mfma_f32_16x16x32_bf16 v[4:7], v[146:149], v[198:201], v[4:7]
	v_mfma_f32_16x16x32_bf16 v[100:103], v[154:157], v[198:201], v[100:103]
	v_mfma_f32_16x16x32_bf16 v[104:107], v[146:149], v[206:209], v[104:107]
	v_mfma_f32_16x16x32_bf16 v[108:111], v[154:157], v[206:209], v[108:111]
	v_mfma_f32_16x16x32_bf16 v[112:115], v[146:149], v[214:217], v[112:115]
	v_mfma_f32_16x16x32_bf16 v[116:119], v[154:157], v[214:217], v[116:119]
	v_mfma_f32_16x16x32_bf16 v[120:123], v[146:149], v[222:225], v[120:123]
	v_mfma_f32_16x16x32_bf16 v[124:127], v[154:157], v[222:225], v[124:127]
	s_setprio 0
	s_setprio 1
	v_mfma_f32_16x16x32_bf16 v[68:71], v[186:189], v[194:197], v[68:71]
	v_mfma_f32_16x16x32_bf16 v[72:75], v[158:161], v[202:205], v[72:75]
	v_mfma_f32_16x16x32_bf16 v[76:79], v[186:189], v[202:205], v[76:79]
	v_mfma_f32_16x16x32_bf16 v[80:83], v[158:161], v[210:213], v[80:83]
	v_mfma_f32_16x16x32_bf16 v[84:87], v[186:189], v[210:213], v[84:87]
	v_mfma_f32_16x16x32_bf16 v[88:91], v[158:161], v[218:221], v[88:91]
	v_mfma_f32_16x16x32_bf16 v[130:133], v[158:161], v[194:197], v[134:137]
	v_mfma_f32_16x16x32_bf16 v[68:71], v[190:193], v[198:201], v[68:71]
	v_mfma_f32_16x16x32_bf16 v[72:75], v[162:165], v[206:209], v[72:75]
	v_mfma_f32_16x16x32_bf16 v[76:79], v[190:193], v[206:209], v[76:79]
	v_mfma_f32_16x16x32_bf16 v[80:83], v[162:165], v[214:217], v[80:83]
	v_mfma_f32_16x16x32_bf16 v[84:87], v[190:193], v[214:217], v[84:87]
	v_mfma_f32_16x16x32_bf16 v[134:137], v[162:165], v[222:225], v[88:91]
	v_mfma_f32_16x16x32_bf16 v[88:91], v[186:189], v[218:221], v[92:95]
	v_mfma_f32_16x16x32_bf16 v[130:133], v[162:165], v[198:201], v[130:133]
	v_mfma_f32_16x16x32_bf16 v[194:197], v[190:193], v[222:225], v[88:91]
	s_setprio 0
	s_barrier
	s_mov_b32 m0, s30
	s_nop 2
	ds_read_b128 v[88:91], v246 offset:16384
	ds_read_b128 v[92:95], v246 offset:17408
	ds_read_b128 v[198:201], v246 offset:18432
	ds_read_b128 v[202:205], v246 offset:19456
	ds_read_b128 v[206:209], v246 offset:20480
	ds_read_b128 v[210:213], v246 offset:21504
	ds_read_b128 v[214:217], v246 offset:22528
	ds_read_b128 v[218:221], v246 offset:23552
	global_load_lds_dwordx4 v[16:17], off
	s_mov_b32 m0, s29
	s_nop 0
	global_load_lds_dwordx4 v[18:19], off
	s_mov_b32 m0, s33
	s_nop 0
	global_load_lds_dwordx4 v[14:15], off
	s_mov_b32 m0, s31
	s_nop 0
	global_load_lds_dwordx4 v[8:9], off
	s_mov_b32 m0, s27
	s_nop 0
	global_load_lds_dwordx4 v[10:11], off
	s_mov_b32 m0, s28
	s_nop 0
	global_load_lds_dwordx4 v[12:13], off
	s_waitcnt vmcnt(8)
	s_waitcnt lgkmcnt(0)
	s_barrier
	s_setprio 1
	s_waitcnt lgkmcnt(0)
	v_mfma_f32_16x16x32_bf16 v[8:11], v[142:145], v[88:91], v[20:23]
	v_mfma_f32_16x16x32_bf16 v[222:225], v[146:149], v[92:95], v[8:11]
	v_mfma_f32_16x16x32_bf16 v[8:11], v[150:153], v[88:91], v[166:169]
	v_mfma_f32_16x16x32_bf16 v[166:169], v[154:157], v[92:95], v[8:11]
	v_mfma_f32_16x16x32_bf16 v[8:11], v[142:145], v[198:201], v[170:173]
	v_mfma_f32_16x16x32_bf16 v[170:173], v[146:149], v[202:205], v[8:11]
	v_mfma_f32_16x16x32_bf16 v[8:11], v[150:153], v[198:201], v[174:177]
	v_mfma_f32_16x16x32_bf16 v[174:177], v[154:157], v[202:205], v[8:11]
	v_mfma_f32_16x16x32_bf16 v[8:11], v[142:145], v[206:209], v[178:181]
	v_mfma_f32_16x16x32_bf16 v[178:181], v[146:149], v[210:213], v[8:11]
	v_mfma_f32_16x16x32_bf16 v[8:11], v[150:153], v[206:209], v[182:185]
	v_mfma_f32_16x16x32_bf16 v[182:185], v[154:157], v[210:213], v[8:11]
	v_mfma_f32_16x16x32_bf16 v[8:11], v[142:145], v[214:217], v[24:27]
	v_mfma_f32_16x16x32_bf16 v[142:145], v[146:149], v[218:221], v[8:11]
	v_mfma_f32_16x16x32_bf16 v[8:11], v[150:153], v[214:217], v[32:35]
	v_mfma_f32_16x16x32_bf16 v[146:149], v[154:157], v[218:221], v[8:11]
	s_setprio 0
	s_setprio 1
	v_mfma_f32_16x16x32_bf16 v[8:11], v[158:161], v[88:91], v[40:43]
	v_mfma_f32_16x16x32_bf16 v[150:153], v[162:165], v[92:95], v[8:11]
	v_mfma_f32_16x16x32_bf16 v[8:11], v[186:189], v[88:91], v[44:47]
	v_mfma_f32_16x16x32_bf16 v[154:157], v[190:193], v[92:95], v[8:11]
	v_mfma_f32_16x16x32_bf16 v[8:11], v[158:161], v[198:201], v[60:63]
	v_mfma_f32_16x16x32_bf16 v[226:229], v[162:165], v[202:205], v[8:11]
	v_mfma_f32_16x16x32_bf16 v[8:11], v[186:189], v[198:201], v[64:67]
	v_mfma_f32_16x16x32_bf16 v[198:201], v[190:193], v[202:205], v[8:11]
	v_mfma_f32_16x16x32_bf16 v[8:11], v[158:161], v[206:209], v[96:99]
	v_mfma_f32_16x16x32_bf16 v[202:205], v[162:165], v[210:213], v[8:11]
	v_mfma_f32_16x16x32_bf16 v[8:11], v[186:189], v[206:209], v[138:141]
	v_mfma_f32_16x16x32_bf16 v[138:141], v[190:193], v[210:213], v[8:11]
	v_mfma_f32_16x16x32_bf16 v[8:11], v[158:161], v[214:217], v[48:51]
	v_mfma_f32_16x16x32_bf16 v[158:161], v[162:165], v[218:221], v[8:11]
	v_mfma_f32_16x16x32_bf16 v[8:11], v[186:189], v[214:217], v[56:59]
	v_mfma_f32_16x16x32_bf16 v[162:165], v[190:193], v[218:221], v[8:11]
	s_setprio 0
	s_barrier
	ds_read_b128 v[186:189], v234
	ds_read_b128 v[190:193], v234 offset:1024
	ds_read_b128 v[206:209], v234 offset:2048
	ds_read_b128 v[210:213], v234 offset:3072
	ds_read_b128 v[214:217], v235
	ds_read_b128 v[218:221], v235 offset:1024
	ds_read_b128 v[230:233], v235 offset:2048
	ds_read_b128 v[234:237], v235 offset:3072
	s_mov_b32 m0, s23
	ds_read_b128 v[24:27], v246 offset:32768
	ds_read_b128 v[32:35], v246 offset:33792
	ds_read_b128 v[48:51], v246 offset:34816
	ds_read_b128 v[56:59], v246 offset:35840
	ds_read_b128 v[60:63], v246 offset:36864
	ds_read_b128 v[96:99], v246 offset:37888
	ds_read_b128 v[238:241], v246 offset:38912
	ds_read_b128 v[242:245], v246 offset:39936
	global_load_lds_dwordx4 v[0:1], off
	s_mov_b32 m0, s24
	s_nop 0
	global_load_lds_dwordx4 v[2:3], off
	s_waitcnt vmcnt(8)
	s_waitcnt lgkmcnt(0)
	s_barrier
	s_setprio 1
	s_waitcnt lgkmcnt(0)
	v_mfma_f32_16x16x32_bf16 v[0:3], v[186:189], v[24:27], v[4:7]
	v_mfma_f32_16x16x32_bf16 v[40:43], v[190:193], v[32:35], v[0:3]
	v_mfma_f32_16x16x32_bf16 v[0:3], v[206:209], v[24:27], v[100:103]
	v_mfma_f32_16x16x32_bf16 v[44:47], v[210:213], v[32:35], v[0:3]
	v_mfma_f32_16x16x32_bf16 v[0:3], v[186:189], v[48:51], v[104:107]
	v_mfma_f32_16x16x32_bf16 v[16:19], v[190:193], v[56:59], v[0:3]
	v_mfma_f32_16x16x32_bf16 v[0:3], v[206:209], v[48:51], v[108:111]
	v_mfma_f32_16x16x32_bf16 v[20:23], v[210:213], v[56:59], v[0:3]
	v_mfma_f32_16x16x32_bf16 v[0:3], v[186:189], v[60:63], v[112:115]
	v_mfma_f32_16x16x32_bf16 v[8:11], v[190:193], v[96:99], v[0:3]
	v_mfma_f32_16x16x32_bf16 v[0:3], v[206:209], v[60:63], v[116:119]
	v_mfma_f32_16x16x32_bf16 v[12:15], v[210:213], v[96:99], v[0:3]
	v_mfma_f32_16x16x32_bf16 v[0:3], v[186:189], v[238:241], v[120:123]
	v_mfma_f32_16x16x32_bf16 v[4:7], v[206:209], v[238:241], v[124:127]
	v_mfma_f32_16x16x32_bf16 v[0:3], v[190:193], v[242:245], v[0:3]
	v_mfma_f32_16x16x32_bf16 v[4:7], v[210:213], v[242:245], v[4:7]
	s_setprio 0
	s_setprio 1
	v_mfma_f32_16x16x32_bf16 v[64:67], v[214:217], v[24:27], v[130:133]
	v_mfma_f32_16x16x32_bf16 v[24:27], v[230:233], v[24:27], v[68:71]
	v_mfma_f32_16x16x32_bf16 v[92:95], v[234:237], v[32:35], v[24:27]
	v_mfma_f32_16x16x32_bf16 v[24:27], v[214:217], v[48:51], v[72:75]
	v_mfma_f32_16x16x32_bf16 v[88:91], v[218:221], v[32:35], v[64:67]
	v_mfma_f32_16x16x32_bf16 v[64:67], v[218:221], v[56:59], v[24:27]
	v_mfma_f32_16x16x32_bf16 v[24:27], v[230:233], v[48:51], v[76:79]
	v_mfma_f32_16x16x32_bf16 v[68:71], v[234:237], v[56:59], v[24:27]
	v_mfma_f32_16x16x32_bf16 v[24:27], v[214:217], v[60:63], v[80:83]
	v_mfma_f32_16x16x32_bf16 v[48:51], v[218:221], v[96:99], v[24:27]
	v_mfma_f32_16x16x32_bf16 v[24:27], v[230:233], v[60:63], v[84:87]
	v_mfma_f32_16x16x32_bf16 v[56:59], v[234:237], v[96:99], v[24:27]
	v_mfma_f32_16x16x32_bf16 v[24:27], v[214:217], v[238:241], v[134:137]
	v_mfma_f32_16x16x32_bf16 v[32:35], v[230:233], v[238:241], v[194:197]
	v_mfma_f32_16x16x32_bf16 v[24:27], v[218:221], v[242:245], v[24:27]
	v_mfma_f32_16x16x32_bf16 v[32:35], v[234:237], v[242:245], v[32:35]
	s_setprio 0
	s_barrier
	s_mov_b32 m0, s17
	ds_read_b128 v[80:83], v246 offset:49152
	ds_read_b128 v[84:87], v246 offset:50176
	ds_read_b128 v[104:107], v246 offset:51200
	ds_read_b128 v[108:111], v246 offset:52224
	ds_read_b128 v[130:133], v246 offset:53248
	ds_read_b128 v[134:137], v246 offset:54272
	ds_read_b128 v[194:197], v246 offset:55296
	ds_read_b128 v[238:241], v246 offset:56320
	global_load_lds_dwordx4 v[30:31], off
	s_mov_b32 m0, s19
	s_nop 0
	global_load_lds_dwordx4 v[36:37], off
	s_mov_b32 m0, s25
	s_nop 0
	global_load_lds_dwordx4 v[52:53], off
	s_mov_b32 m0, s26
	s_nop 0
	global_load_lds_dwordx4 v[54:55], off
	s_mov_b32 m0, s18
	s_nop 0
	global_load_lds_dwordx4 v[28:29], off
	s_mov_b32 m0, s22
	s_nop 0
	global_load_lds_dwordx4 v[38:39], off
	s_waitcnt vmcnt(8)
	s_waitcnt lgkmcnt(0)
	s_barrier
	s_setprio 1
	s_waitcnt lgkmcnt(0)
	v_mfma_f32_16x16x32_bf16 v[28:31], v[186:189], v[80:83], v[222:225]
	v_mfma_f32_16x16x32_bf16 v[96:99], v[190:193], v[84:87], v[28:31]
	v_mfma_f32_16x16x32_bf16 v[28:31], v[206:209], v[80:83], v[166:169]
	v_mfma_f32_16x16x32_bf16 v[100:103], v[210:213], v[84:87], v[28:31]
	v_mfma_f32_16x16x32_bf16 v[28:31], v[186:189], v[104:107], v[170:173]
	v_mfma_f32_16x16x32_bf16 v[72:75], v[190:193], v[108:111], v[28:31]
	v_mfma_f32_16x16x32_bf16 v[28:31], v[206:209], v[104:107], v[174:177]
	v_mfma_f32_16x16x32_bf16 v[76:79], v[210:213], v[108:111], v[28:31]
	v_mfma_f32_16x16x32_bf16 v[28:31], v[186:189], v[130:133], v[178:181]
	v_mfma_f32_16x16x32_bf16 v[52:55], v[190:193], v[134:137], v[28:31]
	v_mfma_f32_16x16x32_bf16 v[28:31], v[206:209], v[130:133], v[182:185]
	v_mfma_f32_16x16x32_bf16 v[60:63], v[210:213], v[134:137], v[28:31]
	v_mfma_f32_16x16x32_bf16 v[28:31], v[186:189], v[194:197], v[142:145]
	v_mfma_f32_16x16x32_bf16 v[36:39], v[206:209], v[194:197], v[146:149]
	v_mfma_f32_16x16x32_bf16 v[28:31], v[190:193], v[238:241], v[28:31]
	v_mfma_f32_16x16x32_bf16 v[36:39], v[210:213], v[238:241], v[36:39]
	s_setprio 0
	s_setprio 1
	v_mfma_f32_16x16x32_bf16 v[112:115], v[214:217], v[80:83], v[150:153]
	v_mfma_f32_16x16x32_bf16 v[80:83], v[230:233], v[80:83], v[154:157]
	v_mfma_f32_16x16x32_bf16 v[124:127], v[234:237], v[84:87], v[80:83]
	v_mfma_f32_16x16x32_bf16 v[80:83], v[214:217], v[104:107], v[226:229]
	v_mfma_f32_16x16x32_bf16 v[120:123], v[218:221], v[84:87], v[112:115]
	v_mfma_f32_16x16x32_bf16 v[112:115], v[218:221], v[108:111], v[80:83]
	v_mfma_f32_16x16x32_bf16 v[80:83], v[230:233], v[104:107], v[198:201]
	v_mfma_f32_16x16x32_bf16 v[116:119], v[234:237], v[108:111], v[80:83]
	v_mfma_f32_16x16x32_bf16 v[80:83], v[214:217], v[130:133], v[202:205]
	v_mfma_f32_16x16x32_bf16 v[104:107], v[218:221], v[134:137], v[80:83]
	v_mfma_f32_16x16x32_bf16 v[80:83], v[230:233], v[130:133], v[138:141]
	v_mfma_f32_16x16x32_bf16 v[108:111], v[234:237], v[134:137], v[80:83]
	v_mfma_f32_16x16x32_bf16 v[80:83], v[214:217], v[194:197], v[158:161]
	v_mfma_f32_16x16x32_bf16 v[84:87], v[230:233], v[194:197], v[162:165]
	v_mfma_f32_16x16x32_bf16 v[80:83], v[218:221], v[238:241], v[80:83]
	v_mfma_f32_16x16x32_bf16 v[84:87], v[234:237], v[238:241], v[84:87]
	s_setprio 0
	s_barrier
	s_cbranch_scc1 .LBB0_723
	s_barrier
